# attention O epilogue: 8 dwordx4 stores per lane via v_permlane32_swap pairs instead of 16 dwordx2
# speedup vs baseline: 1.0015x; 1.0015x over previous
.LBB0_1711:
	s_or_b64 exec, exec, s[4:5]
	ds_bpermute_b32 v66, v169, v170
	v_lshl_add_u64 v[64:65], v[148:149], 1, s[40:41]
	v_lshlrev_b32_e32 v144, 1, v147
	v_lshl_add_u64 v[64:65], v[64:65], 0, s[42:43]
	v_lshl_add_u64 v[64:65], v[64:65], 0, v[144:145]
	s_waitcnt lgkmcnt(0)
	v_add_f32_e32 v66, v170, v66
	v_div_scale_f32 v67, s[0:1], v66, v66, 1.0
	v_rcp_f32_e32 v68, v67
	v_div_scale_f32 v69, vcc, 1.0, v66, 1.0
	s_add_i32 s53, s53, s90
	v_fma_f32 v70, -v67, v68, 1.0
	v_fmac_f32_e32 v68, v70, v68
	v_mul_f32_e32 v70, v69, v68
	v_fma_f32 v71, -v67, v70, v69
	v_fmac_f32_e32 v70, v71, v68
	v_fma_f32 v67, -v67, v70, v69
	v_div_fmas_f32 v67, v67, v68, v70
	v_div_fixup_f32 v66, v67, v66, 1.0
	v_mbcnt_lo_u32_b32 v208, -1, 0
	v_mbcnt_hi_u32_b32 v208, -1, v208
	v_and_b32_e32 v208, 32, v208
	v_lshrrev_b32_e32 v208, 2, v208
	v_mov_b32_e32 v209, 0
	v_lshl_add_u64 v[64:65], v[64:65], 0, v[208:209]
	v_pk_mul_f32 v[48:49], v[48:49], v[66:67] op_sel_hi:[1,0]
	v_pk_mul_f32 v[50:51], v[50:51], v[66:67] op_sel_hi:[1,0]
	v_pk_mul_f32 v[52:53], v[52:53], v[66:67] op_sel_hi:[1,0]
	v_pk_mul_f32 v[54:55], v[54:55], v[66:67] op_sel_hi:[1,0]
	v_cvt_pk_bf16_f32 v48, v48, v49
	v_cvt_pk_bf16_f32 v49, v50, v51
	v_cvt_pk_bf16_f32 v50, v52, v53
	v_cvt_pk_bf16_f32 v51, v54, v55
	s_nop 1
	v_permlane32_swap_b32_e32 v48, v50
	v_permlane32_swap_b32_e32 v49, v51
	global_store_dwordx4 v[64:65], v[48:51], off
	v_pk_mul_f32 v[56:57], v[56:57], v[66:67] op_sel_hi:[1,0]
	v_pk_mul_f32 v[58:59], v[58:59], v[66:67] op_sel_hi:[1,0]
	v_pk_mul_f32 v[60:61], v[60:61], v[66:67] op_sel_hi:[1,0]
	v_pk_mul_f32 v[62:63], v[62:63], v[66:67] op_sel_hi:[1,0]
	v_cvt_pk_bf16_f32 v56, v56, v57
	v_cvt_pk_bf16_f32 v57, v58, v59
	v_cvt_pk_bf16_f32 v58, v60, v61
	v_cvt_pk_bf16_f32 v59, v62, v63
	s_nop 1
	v_permlane32_swap_b32_e32 v56, v58
	v_permlane32_swap_b32_e32 v57, v59
	global_store_dwordx4 v[64:65], v[56:59], off offset:32
	v_pk_mul_f32 v[32:33], v[32:33], v[66:67] op_sel_hi:[1,0]
	v_pk_mul_f32 v[34:35], v[34:35], v[66:67] op_sel_hi:[1,0]
	v_pk_mul_f32 v[36:37], v[36:37], v[66:67] op_sel_hi:[1,0]
	v_pk_mul_f32 v[38:39], v[38:39], v[66:67] op_sel_hi:[1,0]
	v_cvt_pk_bf16_f32 v32, v32, v33
	v_cvt_pk_bf16_f32 v33, v34, v35
	v_cvt_pk_bf16_f32 v34, v36, v37
	v_cvt_pk_bf16_f32 v35, v38, v39
	s_nop 1
	v_permlane32_swap_b32_e32 v32, v34
	v_permlane32_swap_b32_e32 v33, v35
	global_store_dwordx4 v[64:65], v[32:35], off offset:64
	v_pk_mul_f32 v[40:41], v[40:41], v[66:67] op_sel_hi:[1,0]
	v_pk_mul_f32 v[42:43], v[42:43], v[66:67] op_sel_hi:[1,0]
	v_pk_mul_f32 v[44:45], v[44:45], v[66:67] op_sel_hi:[1,0]
	v_pk_mul_f32 v[46:47], v[46:47], v[66:67] op_sel_hi:[1,0]
	v_cvt_pk_bf16_f32 v40, v40, v41
	v_cvt_pk_bf16_f32 v41, v42, v43
	v_cvt_pk_bf16_f32 v42, v44, v45
	v_cvt_pk_bf16_f32 v43, v46, v47
	s_nop 1
	v_permlane32_swap_b32_e32 v40, v42
	v_permlane32_swap_b32_e32 v41, v43
	global_store_dwordx4 v[64:65], v[40:43], off offset:96
	v_pk_mul_f32 v[16:17], v[16:17], v[66:67] op_sel_hi:[1,0]
	v_pk_mul_f32 v[18:19], v[18:19], v[66:67] op_sel_hi:[1,0]
	v_pk_mul_f32 v[20:21], v[20:21], v[66:67] op_sel_hi:[1,0]
	v_pk_mul_f32 v[22:23], v[22:23], v[66:67] op_sel_hi:[1,0]
	v_cvt_pk_bf16_f32 v16, v16, v17
	v_cvt_pk_bf16_f32 v17, v18, v19
	v_cvt_pk_bf16_f32 v18, v20, v21
	v_cvt_pk_bf16_f32 v19, v22, v23
	s_nop 1
	v_permlane32_swap_b32_e32 v16, v18
	v_permlane32_swap_b32_e32 v17, v19
	global_store_dwordx4 v[64:65], v[16:19], off offset:128
	v_pk_mul_f32 v[24:25], v[24:25], v[66:67] op_sel_hi:[1,0]
	v_pk_mul_f32 v[26:27], v[26:27], v[66:67] op_sel_hi:[1,0]
	v_pk_mul_f32 v[28:29], v[28:29], v[66:67] op_sel_hi:[1,0]
	v_pk_mul_f32 v[30:31], v[30:31], v[66:67] op_sel_hi:[1,0]
	v_cvt_pk_bf16_f32 v24, v24, v25
	v_cvt_pk_bf16_f32 v25, v26, v27
	v_cvt_pk_bf16_f32 v26, v28, v29
	v_cvt_pk_bf16_f32 v27, v30, v31
	s_nop 1
	v_permlane32_swap_b32_e32 v24, v26
	v_permlane32_swap_b32_e32 v25, v27
	global_store_dwordx4 v[64:65], v[24:27], off offset:160
	v_pk_mul_f32 v[0:1], v[0:1], v[66:67] op_sel_hi:[1,0]
	v_pk_mul_f32 v[2:3], v[2:3], v[66:67] op_sel_hi:[1,0]
	v_pk_mul_f32 v[4:5], v[4:5], v[66:67] op_sel_hi:[1,0]
	v_pk_mul_f32 v[6:7], v[6:7], v[66:67] op_sel_hi:[1,0]
	v_cvt_pk_bf16_f32 v0, v0, v1
	v_cvt_pk_bf16_f32 v1, v2, v3
	v_cvt_pk_bf16_f32 v2, v4, v5
	v_cvt_pk_bf16_f32 v3, v6, v7
	s_nop 1
	v_permlane32_swap_b32_e32 v0, v2
	v_permlane32_swap_b32_e32 v1, v3
	global_store_dwordx4 v[64:65], v[0:3], off offset:192
	v_pk_mul_f32 v[8:9], v[8:9], v[66:67] op_sel_hi:[1,0]
	v_pk_mul_f32 v[10:11], v[10:11], v[66:67] op_sel_hi:[1,0]
	v_pk_mul_f32 v[12:13], v[12:13], v[66:67] op_sel_hi:[1,0]
	v_pk_mul_f32 v[14:15], v[14:15], v[66:67] op_sel_hi:[1,0]
	v_cvt_pk_bf16_f32 v8, v8, v9
	v_cvt_pk_bf16_f32 v9, v10, v11
	v_cvt_pk_bf16_f32 v10, v12, v13
	v_cvt_pk_bf16_f32 v11, v14, v15
	s_nop 1
	v_permlane32_swap_b32_e32 v8, v10
	v_permlane32_swap_b32_e32 v9, v11
	global_store_dwordx4 v[64:65], v[8:11], off offset:224
	s_add_i32 s2, s2, s90
	s_cmpk_gt_i32 s53, 0xff
	s_cbranch_scc1 .LBB0_1794

.LBB0_1752:
	s_or_b64 exec, exec, s[4:5]
	ds_bpermute_b32 v66, v169, v170
	v_lshl_add_u64 v[64:65], v[148:149], 1, s[40:41]
	v_lshlrev_b32_e32 v144, 1, v147
	v_lshl_add_u64 v[64:65], v[64:65], 0, s[42:43]
	v_lshl_add_u64 v[64:65], v[64:65], 0, v[144:145]
	s_waitcnt lgkmcnt(0)
	v_add_f32_e32 v66, v170, v66
	v_div_scale_f32 v67, s[0:1], v66, v66, 1.0
	v_rcp_f32_e32 v68, v67
	v_div_scale_f32 v69, vcc, 1.0, v66, 1.0
	s_lshl_b32 s0, s80, 8
	v_fma_f32 v70, -v67, v68, 1.0
	v_fmac_f32_e32 v68, v70, v68
	v_mul_f32_e32 v70, v69, v68
	v_fma_f32 v71, -v67, v70, v69
	v_fmac_f32_e32 v70, v71, v68
	v_fma_f32 v67, -v67, v70, v69
	v_div_fmas_f32 v67, v67, v68, v70
	v_div_fixup_f32 v66, v67, v66, 1.0
	v_mbcnt_lo_u32_b32 v208, -1, 0
	v_mbcnt_hi_u32_b32 v208, -1, v208
	v_and_b32_e32 v208, 32, v208
	v_lshrrev_b32_e32 v208, 2, v208
	v_mov_b32_e32 v209, 0
	v_lshl_add_u64 v[64:65], v[64:65], 0, v[208:209]
	v_pk_mul_f32 v[48:49], v[48:49], v[66:67] op_sel_hi:[1,0]
	v_pk_mul_f32 v[50:51], v[50:51], v[66:67] op_sel_hi:[1,0]
	v_pk_mul_f32 v[52:53], v[52:53], v[66:67] op_sel_hi:[1,0]
	v_pk_mul_f32 v[54:55], v[54:55], v[66:67] op_sel_hi:[1,0]
	v_cvt_pk_bf16_f32 v48, v48, v49
	v_cvt_pk_bf16_f32 v49, v50, v51
	v_cvt_pk_bf16_f32 v50, v52, v53
	v_cvt_pk_bf16_f32 v51, v54, v55
	s_nop 1
	v_permlane32_swap_b32_e32 v48, v50
	v_permlane32_swap_b32_e32 v49, v51
	global_store_dwordx4 v[64:65], v[48:51], off
	v_pk_mul_f32 v[56:57], v[56:57], v[66:67] op_sel_hi:[1,0]
	v_pk_mul_f32 v[58:59], v[58:59], v[66:67] op_sel_hi:[1,0]
	v_pk_mul_f32 v[60:61], v[60:61], v[66:67] op_sel_hi:[1,0]
	v_pk_mul_f32 v[62:63], v[62:63], v[66:67] op_sel_hi:[1,0]
	v_cvt_pk_bf16_f32 v56, v56, v57
	v_cvt_pk_bf16_f32 v57, v58, v59
	v_cvt_pk_bf16_f32 v58, v60, v61
	v_cvt_pk_bf16_f32 v59, v62, v63
	s_nop 1
	v_permlane32_swap_b32_e32 v56, v58
	v_permlane32_swap_b32_e32 v57, v59
	global_store_dwordx4 v[64:65], v[56:59], off offset:32
	v_pk_mul_f32 v[32:33], v[32:33], v[66:67] op_sel_hi:[1,0]
	v_pk_mul_f32 v[34:35], v[34:35], v[66:67] op_sel_hi:[1,0]
	v_pk_mul_f32 v[36:37], v[36:37], v[66:67] op_sel_hi:[1,0]
	v_pk_mul_f32 v[38:39], v[38:39], v[66:67] op_sel_hi:[1,0]
	v_cvt_pk_bf16_f32 v32, v32, v33
	v_cvt_pk_bf16_f32 v33, v34, v35
	v_cvt_pk_bf16_f32 v34, v36, v37
	v_cvt_pk_bf16_f32 v35, v38, v39
	s_nop 1
	v_permlane32_swap_b32_e32 v32, v34
	v_permlane32_swap_b32_e32 v33, v35
	global_store_dwordx4 v[64:65], v[32:35], off offset:64
	v_pk_mul_f32 v[40:41], v[40:41], v[66:67] op_sel_hi:[1,0]
	v_pk_mul_f32 v[42:43], v[42:43], v[66:67] op_sel_hi:[1,0]
	v_pk_mul_f32 v[44:45], v[44:45], v[66:67] op_sel_hi:[1,0]
	v_pk_mul_f32 v[46:47], v[46:47], v[66:67] op_sel_hi:[1,0]
	v_cvt_pk_bf16_f32 v40, v40, v41
	v_cvt_pk_bf16_f32 v41, v42, v43
	v_cvt_pk_bf16_f32 v42, v44, v45
	v_cvt_pk_bf16_f32 v43, v46, v47
	s_nop 1
	v_permlane32_swap_b32_e32 v40, v42
	v_permlane32_swap_b32_e32 v41, v43
	global_store_dwordx4 v[64:65], v[40:43], off offset:96
	v_pk_mul_f32 v[16:17], v[16:17], v[66:67] op_sel_hi:[1,0]
	v_pk_mul_f32 v[18:19], v[18:19], v[66:67] op_sel_hi:[1,0]
	v_pk_mul_f32 v[20:21], v[20:21], v[66:67] op_sel_hi:[1,0]
	v_pk_mul_f32 v[22:23], v[22:23], v[66:67] op_sel_hi:[1,0]
	v_cvt_pk_bf16_f32 v16, v16, v17
	v_cvt_pk_bf16_f32 v17, v18, v19
	v_cvt_pk_bf16_f32 v18, v20, v21
	v_cvt_pk_bf16_f32 v19, v22, v23
	s_nop 1
	v_permlane32_swap_b32_e32 v16, v18
	v_permlane32_swap_b32_e32 v17, v19
	global_store_dwordx4 v[64:65], v[16:19], off offset:128
	v_pk_mul_f32 v[24:25], v[24:25], v[66:67] op_sel_hi:[1,0]
	v_pk_mul_f32 v[26:27], v[26:27], v[66:67] op_sel_hi:[1,0]
	v_pk_mul_f32 v[28:29], v[28:29], v[66:67] op_sel_hi:[1,0]
	v_pk_mul_f32 v[30:31], v[30:31], v[66:67] op_sel_hi:[1,0]
	v_cvt_pk_bf16_f32 v24, v24, v25
	v_cvt_pk_bf16_f32 v25, v26, v27
	v_cvt_pk_bf16_f32 v26, v28, v29
	v_cvt_pk_bf16_f32 v27, v30, v31
	s_nop 1
	v_permlane32_swap_b32_e32 v24, v26
	v_permlane32_swap_b32_e32 v25, v27
	global_store_dwordx4 v[64:65], v[24:27], off offset:160
	v_pk_mul_f32 v[0:1], v[0:1], v[66:67] op_sel_hi:[1,0]
	v_pk_mul_f32 v[2:3], v[2:3], v[66:67] op_sel_hi:[1,0]
	v_pk_mul_f32 v[4:5], v[4:5], v[66:67] op_sel_hi:[1,0]
	v_pk_mul_f32 v[6:7], v[6:7], v[66:67] op_sel_hi:[1,0]
	v_cvt_pk_bf16_f32 v0, v0, v1
	v_cvt_pk_bf16_f32 v1, v2, v3
	v_cvt_pk_bf16_f32 v2, v4, v5
	v_cvt_pk_bf16_f32 v3, v6, v7
	s_nop 1
	v_permlane32_swap_b32_e32 v0, v2
	v_permlane32_swap_b32_e32 v1, v3
	global_store_dwordx4 v[64:65], v[0:3], off offset:192
	v_pk_mul_f32 v[8:9], v[8:9], v[66:67] op_sel_hi:[1,0]
	v_pk_mul_f32 v[10:11], v[10:11], v[66:67] op_sel_hi:[1,0]
	v_pk_mul_f32 v[12:13], v[12:13], v[66:67] op_sel_hi:[1,0]
	v_pk_mul_f32 v[14:15], v[14:15], v[66:67] op_sel_hi:[1,0]
	v_cvt_pk_bf16_f32 v8, v8, v9
	v_cvt_pk_bf16_f32 v9, v10, v11
	v_cvt_pk_bf16_f32 v10, v12, v13
	v_cvt_pk_bf16_f32 v11, v14, v15
	s_nop 1
	v_permlane32_swap_b32_e32 v8, v10
	v_permlane32_swap_b32_e32 v9, v11
	global_store_dwordx4 v[64:65], v[8:11], off offset:224
	v_mov_b32_e32 v0, v236
	s_nop 0
	v_ashrrev_i32_e32 v1, 31, v0
	v_lshl_add_u64 v[2:3], v[0:1], 4, s[54:55]
	s_barrier
	global_load_dwordx4 v[4:7], v[2:3], off
	v_lshlrev_b32_e32 v2, 4, v0
	v_add_u32_e32 v3, 0, v2
	v_add_u32_e32 v3, 0x11800, v3
	v_ashrrev_i32_e32 v74, 1, v0
	v_bfi_b32 v146, s26, v74, v0
	v_and_b32_e32 v144, 0x70, v2
	s_or_b32 s62, s62, s0
	v_ashrrev_i32_e32 v147, 31, v146
	v_bfe_u32 v1, v0, 5, 1
	v_mov_b32_e32 v172, 0
	s_waitcnt vmcnt(0)
	ds_write_b128 v3, v[4:7]
	v_ashrrev_i32_e32 v6, 3, v0
	v_ashrrev_i32_e32 v7, 31, v6
	v_lshlrev_b64 v[4:5], 13, v[6:7]
	v_lshl_add_u64 v[8:9], s[56:57], 0, v[4:5]
	v_lshl_add_u64 v[14:15], v[8:9], 0, v[144:145]
	v_lshl_add_u64 v[8:9], s[62:63], 0, v[146:147]
	v_lshlrev_b64 v[10:11], 12, v[8:9]
	v_lshl_add_u64 v[10:11], s[38:39], 0, v[10:11]
	v_lshl_add_u64 v[10:11], v[10:11], 0, s[42:43]
	v_lshlrev_b32_e32 v144, 4, v1
	v_lshl_add_u64 v[26:27], v[10:11], 0, v[144:145]
	s_waitcnt lgkmcnt(0)
	s_barrier
	global_load_dwordx4 v[10:13], v[26:27], off
	global_load_dwordx4 v[20:23], v[26:27], off offset:32
	v_lshlrev_b32_e32 v7, 5, v1
	global_load_dwordx4 v[16:19], v7, s[82:83]
	global_load_dwordx4 v[28:31], v7, s[82:83] offset:16
	global_load_dwordx4 v[32:35], v7, s[82:83] offset:64
	global_load_dwordx4 v[36:39], v7, s[82:83] offset:80
	global_load_dwordx4 v[40:43], v[26:27], off offset:64
	global_load_dwordx4 v[44:47], v7, s[82:83] offset:128
	global_load_dwordx4 v[48:51], v7, s[82:83] offset:144
	global_load_dwordx4 v[52:55], v[26:27], off offset:96
	global_load_dwordx4 v[56:59], v7, s[82:83] offset:208
	global_load_dwordx4 v[60:63], v7, s[82:83] offset:192
	v_ashrrev_i32_e32 v3, 31, v2
	v_add_co_u32_e32 v70, vcc, s85, v14
	v_lshl_add_u64 v[68:69], s[48:49], 0, v[2:3]
	s_nop 0
	v_addc_co_u32_e32 v71, vcc, 0, v15, vcc
	v_lshl_add_u64 v[24:25], s[50:51], 0, v[2:3]
	global_load_dwordx4 v[64:67], v[26:27], off offset:128
	global_load_dwordx4 v[100:103], v[24:25], off
	global_load_dwordx4 v[96:99], v[68:69], off
	global_load_dwordx4 v[104:107], v[14:15], off
	global_load_dwordx4 v[108:111], v[70:71], off
	s_nop 0
	global_load_dwordx4 v[68:71], v7, s[82:83] offset:272
	global_load_dwordx4 v[76:79], v7, s[82:83] offset:256
	global_load_dwordx4 v[80:83], v[26:27], off offset:160
	global_load_dwordx4 v[84:87], v7, s[82:83] offset:336
	global_load_dwordx4 v[88:91], v7, s[82:83] offset:320
	global_load_dwordx4 v[92:95], v[26:27], off offset:192
	s_andn2_b64 vcc, exec, s[64:65]
	s_waitcnt vmcnt(22)
	v_lshlrev_b32_e32 v14, 16, v12
	v_and_b32_e32 v15, 0xffff0000, v12
	v_lshlrev_b32_e32 v12, 16, v13
	v_and_b32_e32 v13, 0xffff0000, v13
	v_lshlrev_b32_e32 v24, 16, v10
	v_and_b32_e32 v25, 0xffff0000, v10
	v_lshlrev_b32_e32 v10, 16, v11
	v_and_b32_e32 v11, 0xffff0000, v11
	s_waitcnt vmcnt(21)
	v_lshlrev_b32_e32 v112, 16, v22
	v_and_b32_e32 v113, 0xffff0000, v22
	v_pk_mul_f32 v[114:115], v[14:15], v[14:15]
	s_waitcnt vmcnt(19)
	v_pk_mul_f32 v[14:15], v[28:29], v[14:15]
	v_pk_mul_f32 v[28:29], v[12:13], v[12:13]
	v_lshlrev_b32_e32 v72, 16, v20
	v_and_b32_e32 v73, 0xffff0000, v20
	v_lshlrev_b32_e32 v120, 16, v21
	v_and_b32_e32 v121, 0xffff0000, v21
	v_lshlrev_b32_e32 v22, 16, v23
	v_pk_mul_f32 v[20:21], v[18:19], v[10:11]
	v_pk_fma_f32 v[134:135], v[10:11], v[10:11], v[28:29]
	v_and_b32_e32 v23, 0xffff0000, v23
	v_pk_mul_f32 v[10:11], v[112:113], v[112:113]
	v_pk_mul_f32 v[16:17], v[16:17], v[24:25]
	v_pk_fma_f32 v[132:133], v[24:25], v[24:25], v[114:115]
	v_pk_fma_f32 v[136:137], v[72:73], v[72:73], v[10:11]
	s_waitcnt vmcnt(17)
	v_pk_mul_f32 v[10:11], v[36:37], v[112:113]
	v_pk_mul_f32 v[24:25], v[22:23], v[22:23]
	global_load_dwordx4 v[112:115], v7, s[82:83] offset:400
	global_load_dwordx4 v[116:119], v7, s[82:83] offset:384
	v_pk_mul_f32 v[18:19], v[30:31], v[12:13]
	v_pk_mul_f32 v[12:13], v[32:33], v[72:73]
	v_pk_fma_f32 v[72:73], v[120:121], v[120:121], v[24:25]
	v_pk_mul_f32 v[24:25], v[34:35], v[120:121]
	global_load_dwordx4 v[120:123], v[26:27], off offset:224
	global_load_dwordx4 v[124:127], v7, s[82:83] offset:464
	global_load_dwordx4 v[128:131], v7, s[82:83] offset:448
	v_add_f32_e32 v7, v132, v133
	v_add_f32_e32 v7, v134, v7
	v_add_f32_e32 v7, v135, v7
	v_add_f32_e32 v7, v7, v136
	s_waitcnt vmcnt(21)
	v_lshlrev_b32_e32 v32, 16, v42
	v_and_b32_e32 v33, 0xffff0000, v42
	v_add_f32_e32 v7, v137, v7
	v_lshlrev_b32_e32 v28, 16, v40
	v_and_b32_e32 v29, 0xffff0000, v40
	v_pk_mul_f32 v[26:27], v[32:33], v[32:33]
	v_add_f32_e32 v7, v72, v7
	v_lshlrev_b32_e32 v34, 16, v43
	v_and_b32_e32 v35, 0xffff0000, v43
	v_pk_fma_f32 v[138:139], v[28:29], v[28:29], v[26:27]
	v_add_f32_e32 v7, v73, v7
	v_lshlrev_b32_e32 v30, 16, v41
	v_and_b32_e32 v31, 0xffff0000, v41
	s_waitcnt vmcnt(20)
	v_pk_mul_f32 v[26:27], v[44:45], v[28:29]
	s_waitcnt vmcnt(19)
	v_pk_mul_f32 v[28:29], v[48:49], v[32:33]
	v_pk_mul_f32 v[32:33], v[34:35], v[34:35]
	v_add_f32_e32 v7, v138, v7
	v_pk_fma_f32 v[140:141], v[30:31], v[30:31], v[32:33]
	s_waitcnt vmcnt(18)
	v_lshlrev_b32_e32 v40, 16, v54
	v_and_b32_e32 v41, 0xffff0000, v54
	v_add_f32_e32 v7, v139, v7
	v_pk_mul_f32 v[32:33], v[46:47], v[30:31]
	v_pk_mul_f32 v[30:31], v[50:51], v[34:35]
	v_lshlrev_b32_e32 v34, 16, v52
	v_and_b32_e32 v35, 0xffff0000, v52
	v_pk_mul_f32 v[36:37], v[40:41], v[40:41]
	v_add_f32_e32 v7, v140, v7
	v_lshlrev_b32_e32 v42, 16, v55
	v_and_b32_e32 v43, 0xffff0000, v55
	v_pk_fma_f32 v[142:143], v[34:35], v[34:35], v[36:37]
	v_add_f32_e32 v7, v141, v7
	v_pk_mul_f32 v[22:23], v[38:39], v[22:23]
	v_lshlrev_b32_e32 v38, 16, v53
	v_and_b32_e32 v39, 0xffff0000, v53
	s_waitcnt vmcnt(16)
	v_pk_mul_f32 v[36:37], v[60:61], v[34:35]
	v_pk_mul_f32 v[34:35], v[56:57], v[40:41]
	v_pk_mul_f32 v[40:41], v[42:43], v[42:43]
	v_add_f32_e32 v7, v142, v7
	v_pk_fma_f32 v[148:149], v[38:39], v[38:39], v[40:41]
	s_waitcnt vmcnt(15)
	v_lshlrev_b32_e32 v48, 16, v66
	v_and_b32_e32 v49, 0xffff0000, v66
	v_add_f32_e32 v7, v143, v7
	v_pk_mul_f32 v[40:41], v[62:63], v[38:39]
	v_pk_mul_f32 v[38:39], v[58:59], v[42:43]
	v_lshlrev_b32_e32 v42, 16, v64
	v_and_b32_e32 v43, 0xffff0000, v64
	v_pk_mul_f32 v[44:45], v[48:49], v[48:49]
	v_add_f32_e32 v7, v148, v7
	v_lshlrev_b32_e32 v50, 16, v67
	v_and_b32_e32 v51, 0xffff0000, v67
	v_pk_fma_f32 v[150:151], v[42:43], v[42:43], v[44:45]
	v_add_f32_e32 v7, v149, v7
	v_lshlrev_b32_e32 v46, 16, v65
	v_and_b32_e32 v47, 0xffff0000, v65
	s_waitcnt vmcnt(9)
	v_pk_mul_f32 v[44:45], v[76:77], v[42:43]
	v_pk_mul_f32 v[42:43], v[68:69], v[48:49]
	v_pk_mul_f32 v[48:49], v[50:51], v[50:51]
	v_add_f32_e32 v7, v150, v7
	v_pk_fma_f32 v[76:77], v[46:47], v[46:47], v[48:49]
	s_waitcnt vmcnt(8)
	v_lshlrev_b32_e32 v56, 16, v82
	v_and_b32_e32 v57, 0xffff0000, v82
	v_add_f32_e32 v7, v151, v7
	v_pk_mul_f32 v[48:49], v[78:79], v[46:47]
	v_pk_mul_f32 v[46:47], v[70:71], v[50:51]
	v_lshlrev_b32_e32 v50, 16, v80
	v_and_b32_e32 v51, 0xffff0000, v80
	v_pk_mul_f32 v[52:53], v[56:57], v[56:57]
	v_add_f32_e32 v7, v76, v7
	v_lshlrev_b32_e32 v58, 16, v83
	v_and_b32_e32 v59, 0xffff0000, v83
	v_pk_fma_f32 v[70:71], v[50:51], v[50:51], v[52:53]
	v_add_f32_e32 v7, v77, v7
	v_lshlrev_b32_e32 v54, 16, v81
	v_and_b32_e32 v55, 0xffff0000, v81
	s_waitcnt vmcnt(6)
	v_pk_mul_f32 v[52:53], v[88:89], v[50:51]
	v_pk_mul_f32 v[50:51], v[84:85], v[56:57]
	v_pk_mul_f32 v[56:57], v[58:59], v[58:59]
	v_add_f32_e32 v7, v70, v7
	v_pk_fma_f32 v[78:79], v[54:55], v[54:55], v[56:57]
	s_waitcnt vmcnt(5)
	v_lshlrev_b32_e32 v64, 16, v94
	v_and_b32_e32 v65, 0xffff0000, v94
	v_add_f32_e32 v7, v71, v7
	v_pk_mul_f32 v[56:57], v[90:91], v[54:55]
	v_pk_mul_f32 v[54:55], v[86:87], v[58:59]
	v_lshlrev_b32_e32 v58, 16, v92
	v_and_b32_e32 v59, 0xffff0000, v92
	v_pk_mul_f32 v[60:61], v[64:65], v[64:65]
	v_add_f32_e32 v7, v78, v7
	v_lshlrev_b32_e32 v66, 16, v95
	v_and_b32_e32 v67, 0xffff0000, v95
	v_pk_fma_f32 v[80:81], v[58:59], v[58:59], v[60:61]
	v_add_f32_e32 v7, v79, v7
	v_lshlrev_b32_e32 v62, 16, v93
	v_and_b32_e32 v63, 0xffff0000, v93
	s_waitcnt vmcnt(3)
	v_pk_mul_f32 v[60:61], v[116:117], v[58:59]
	v_pk_mul_f32 v[58:59], v[112:113], v[64:65]
	v_pk_mul_f32 v[64:65], v[66:67], v[66:67]
	v_add_f32_e32 v7, v80, v7
	v_pk_fma_f32 v[82:83], v[62:63], v[62:63], v[64:65]
	s_waitcnt vmcnt(2)
	v_lshlrev_b32_e32 v86, 16, v122
	v_and_b32_e32 v87, 0xffff0000, v122
	v_add_f32_e32 v7, v81, v7
	v_pk_mul_f32 v[64:65], v[118:119], v[62:63]
	v_pk_mul_f32 v[62:63], v[114:115], v[66:67]
	v_lshlrev_b32_e32 v66, 16, v120
	v_and_b32_e32 v67, 0xffff0000, v120
	v_pk_mul_f32 v[68:69], v[86:87], v[86:87]
	v_add_f32_e32 v7, v82, v7
	v_lshlrev_b32_e32 v88, 16, v123
	v_and_b32_e32 v89, 0xffff0000, v123
	v_pk_fma_f32 v[90:91], v[66:67], v[66:67], v[68:69]
	v_add_f32_e32 v7, v83, v7
	v_lshlrev_b32_e32 v84, 16, v121
	v_and_b32_e32 v85, 0xffff0000, v121
	s_waitcnt vmcnt(0)
	v_pk_mul_f32 v[68:69], v[128:129], v[66:67]
	v_pk_mul_f32 v[66:67], v[124:125], v[86:87]
	v_pk_mul_f32 v[86:87], v[88:89], v[88:89]
	v_add_f32_e32 v7, v90, v7
	v_pk_fma_f32 v[86:87], v[84:85], v[84:85], v[86:87]
	v_add_f32_e32 v7, v91, v7
	v_add_f32_e32 v7, v86, v7
	v_add_f32_e32 v7, v87, v7
	ds_bpermute_b32 v75, v169, v7
	v_pk_mul_f32 v[70:71], v[130:131], v[84:85]
	v_pk_mul_f32 v[72:73], v[126:127], v[88:89]
	s_cbranch_vccnz .LBB0_1769
	v_lshlrev_b32_e32 v76, 3, v1
	v_lshl_add_u32 v76, v76, 2, 0
	v_add_u32_e32 v77, 0x11800, v76
	ds_read_b128 v[80:83], v77
	ds_read_b128 v[84:87], v77 offset:16
	ds_read_b128 v[88:91], v77 offset:64
	ds_read_b128 v[92:95], v77 offset:80
	s_cmp_lg_u32 s80, 1
	v_mov_b32_e32 v78, 0
	s_waitcnt lgkmcnt(3)
	v_fma_f32 v76, v16, v80, 0
	s_waitcnt lgkmcnt(2)
	v_fmac_f32_e32 v76, v14, v84
	v_fmac_f32_e32 v76, v17, v81
	v_fmac_f32_e32 v76, v15, v85
	v_fmac_f32_e32 v76, v20, v82
	v_fmac_f32_e32 v76, v18, v86
	v_fmac_f32_e32 v76, v21, v83
	v_fmac_f32_e32 v76, v19, v87
	s_waitcnt lgkmcnt(1)
	v_fmac_f32_e32 v76, v12, v88
	s_waitcnt lgkmcnt(0)
	v_fmac_f32_e32 v76, v10, v92
	v_fmac_f32_e32 v76, v13, v89
	v_fmac_f32_e32 v76, v11, v93
	v_fmac_f32_e32 v76, v24, v90
	ds_read_b128 v[80:83], v77 offset:128
	ds_read_b128 v[84:87], v77 offset:144
	v_fmac_f32_e32 v76, v22, v94
	v_fmac_f32_e32 v76, v25, v91
	v_fmac_f32_e32 v76, v23, v95
	s_waitcnt lgkmcnt(1)
	v_fmac_f32_e32 v76, v26, v80
	s_waitcnt lgkmcnt(0)
	v_fmac_f32_e32 v76, v28, v84
	v_fmac_f32_e32 v76, v27, v81
	v_fmac_f32_e32 v76, v29, v85
	v_fmac_f32_e32 v76, v32, v82
	ds_read_b128 v[88:91], v77 offset:192
	ds_read_b128 v[92:95], v77 offset:208
	v_fmac_f32_e32 v76, v30, v86
	v_fmac_f32_e32 v76, v33, v83
	v_fmac_f32_e32 v76, v31, v87
	s_waitcnt lgkmcnt(1)
	v_fmac_f32_e32 v76, v36, v88
	s_waitcnt lgkmcnt(0)
	v_fmac_f32_e32 v76, v34, v92
	v_fmac_f32_e32 v76, v37, v89
	v_fmac_f32_e32 v76, v35, v93
	v_fmac_f32_e32 v76, v40, v90
	ds_read_b128 v[80:83], v77 offset:256
	ds_read_b128 v[84:87], v77 offset:272
	v_fmac_f32_e32 v76, v38, v94
	v_fmac_f32_e32 v76, v41, v91
	v_fmac_f32_e32 v76, v39, v95
	s_waitcnt lgkmcnt(1)
	v_fmac_f32_e32 v76, v44, v80
	s_waitcnt lgkmcnt(0)
	v_fmac_f32_e32 v76, v42, v84
	v_fmac_f32_e32 v76, v45, v81
	v_fmac_f32_e32 v76, v43, v85
	v_fmac_f32_e32 v76, v48, v82
	ds_read_b128 v[88:91], v77 offset:320
	ds_read_b128 v[92:95], v77 offset:336
	v_fmac_f32_e32 v76, v46, v86
	v_fmac_f32_e32 v76, v49, v83
	v_fmac_f32_e32 v76, v47, v87
	s_waitcnt lgkmcnt(1)
	v_fmac_f32_e32 v76, v52, v88
	s_waitcnt lgkmcnt(0)
	v_fmac_f32_e32 v76, v50, v92
	v_fmac_f32_e32 v76, v53, v89
	v_fmac_f32_e32 v76, v51, v93
	v_fmac_f32_e32 v76, v56, v90
	ds_read_b128 v[80:83], v77 offset:384
	ds_read_b128 v[84:87], v77 offset:400
	v_fmac_f32_e32 v76, v54, v94
	v_fmac_f32_e32 v76, v57, v91
	v_fmac_f32_e32 v76, v55, v95
	s_waitcnt lgkmcnt(1)
	v_fmac_f32_e32 v76, v60, v80
	s_waitcnt lgkmcnt(0)
	v_fmac_f32_e32 v76, v58, v84
	v_fmac_f32_e32 v76, v61, v81
	v_fmac_f32_e32 v76, v59, v85
	v_fmac_f32_e32 v76, v64, v82
	ds_read_b128 v[88:91], v77 offset:448
	ds_read_b128 v[92:95], v77 offset:464
	v_fmac_f32_e32 v76, v62, v86
	v_fmac_f32_e32 v76, v65, v83
	v_fmac_f32_e32 v76, v63, v87
	s_waitcnt lgkmcnt(1)
	v_fmac_f32_e32 v76, v68, v88
	s_waitcnt lgkmcnt(0)
	v_fmac_f32_e32 v76, v66, v92
	v_fmac_f32_e32 v76, v69, v89
	v_fmac_f32_e32 v76, v67, v93
	v_fmac_f32_e32 v76, v70, v90
	v_fmac_f32_e32 v76, v72, v94
	v_fmac_f32_e32 v76, v71, v91
	v_fmac_f32_e32 v76, v73, v95
	ds_bpermute_b32 v79, v169, v76
	s_cselect_b64 s[14:15], -1, 0
	s_cmp_eq_u32 s80, 1
	v_mov_b32_e32 v80, 0
	s_cbranch_scc1 .LBB0_1755
	ds_read_b128 v[80:83], v77 offset:512
	ds_read_b128 v[84:87], v77 offset:528
	ds_read_b128 v[88:91], v77 offset:576
	ds_read_b128 v[92:95], v77 offset:592
	s_waitcnt lgkmcnt(3)
	v_fma_f32 v112, v16, v80, 0
	s_waitcnt lgkmcnt(2)
	v_fmac_f32_e32 v112, v14, v84
	v_fmac_f32_e32 v112, v17, v81
	v_fmac_f32_e32 v112, v15, v85
	v_fmac_f32_e32 v112, v20, v82
	v_fmac_f32_e32 v112, v18, v86
	v_fmac_f32_e32 v112, v21, v83
	v_fmac_f32_e32 v112, v19, v87
	s_waitcnt lgkmcnt(1)
	v_fmac_f32_e32 v112, v12, v88
	s_waitcnt lgkmcnt(0)
	v_fmac_f32_e32 v112, v10, v92
	v_fmac_f32_e32 v112, v13, v89
	v_fmac_f32_e32 v112, v11, v93
	v_fmac_f32_e32 v112, v24, v90
	ds_read_b128 v[80:83], v77 offset:640
	ds_read_b128 v[84:87], v77 offset:656
	v_fmac_f32_e32 v112, v22, v94
	v_fmac_f32_e32 v112, v25, v91
	v_fmac_f32_e32 v112, v23, v95
	s_waitcnt lgkmcnt(1)
	v_fmac_f32_e32 v112, v26, v80
	s_waitcnt lgkmcnt(0)
	v_fmac_f32_e32 v112, v28, v84
	v_fmac_f32_e32 v112, v27, v81
	v_fmac_f32_e32 v112, v29, v85
	v_fmac_f32_e32 v112, v32, v82
	ds_read_b128 v[88:91], v77 offset:704
	ds_read_b128 v[92:95], v77 offset:720
	v_fmac_f32_e32 v112, v30, v86
	v_fmac_f32_e32 v112, v33, v83
	v_fmac_f32_e32 v112, v31, v87
	s_waitcnt lgkmcnt(1)
	v_fmac_f32_e32 v112, v36, v88
	s_waitcnt lgkmcnt(0)
	v_fmac_f32_e32 v112, v34, v92
	v_fmac_f32_e32 v112, v37, v89
	v_fmac_f32_e32 v112, v35, v93
	v_fmac_f32_e32 v112, v40, v90
	ds_read_b128 v[80:83], v77 offset:768
	ds_read_b128 v[84:87], v77 offset:784
	v_fmac_f32_e32 v112, v38, v94
	v_fmac_f32_e32 v112, v41, v91
	v_fmac_f32_e32 v112, v39, v95
	s_waitcnt lgkmcnt(1)
	v_fmac_f32_e32 v112, v44, v80
	s_waitcnt lgkmcnt(0)
	v_fmac_f32_e32 v112, v42, v84
	v_fmac_f32_e32 v112, v45, v81
	v_fmac_f32_e32 v112, v43, v85
	v_fmac_f32_e32 v112, v48, v82
	ds_read_b128 v[88:91], v77 offset:832
	ds_read_b128 v[92:95], v77 offset:848
	v_fmac_f32_e32 v112, v46, v86
	v_fmac_f32_e32 v112, v49, v83
	v_fmac_f32_e32 v112, v47, v87
	s_waitcnt lgkmcnt(1)
	v_fmac_f32_e32 v112, v52, v88
	s_waitcnt lgkmcnt(0)
	v_fmac_f32_e32 v112, v50, v92
	v_fmac_f32_e32 v112, v53, v89
	v_fmac_f32_e32 v112, v51, v93
	v_fmac_f32_e32 v112, v56, v90
	ds_read_b128 v[80:83], v77 offset:896
	ds_read_b128 v[84:87], v77 offset:912
	v_fmac_f32_e32 v112, v54, v94
	v_fmac_f32_e32 v112, v57, v91
	v_fmac_f32_e32 v112, v55, v95
	s_waitcnt lgkmcnt(1)
	v_fmac_f32_e32 v112, v60, v80
	s_waitcnt lgkmcnt(0)
	v_fmac_f32_e32 v112, v58, v84
	v_fmac_f32_e32 v112, v61, v81
	v_fmac_f32_e32 v112, v59, v85
	v_mov_b32_e32 v80, v62
	v_mov_b32_e32 v81, v64
	v_mov_b32_e32 v84, v86
	v_mov_b32_e32 v85, v82
	v_pk_mul_f32 v[80:81], v[80:81], v[84:85]
	v_mov_b32_e32 v82, v87
	v_add_f32_e32 v81, v81, v112
	v_add_f32_e32 v90, v80, v81
	v_mov_b32_e32 v80, v63
	v_mov_b32_e32 v81, v65
	v_pk_mul_f32 v[88:89], v[80:81], v[82:83]
	ds_read_b128 v[80:83], v77 offset:960
	ds_read_b128 v[84:87], v77 offset:976
	v_add_f32_e32 v89, v89, v90
	v_add_f32_e32 v92, v88, v89
	v_mov_b32_e32 v88, v66
	v_mov_b32_e32 v89, v68
	s_waitcnt lgkmcnt(0)
	v_mov_b32_e32 v90, v84
	v_mov_b32_e32 v91, v80
	v_pk_mul_f32 v[88:89], v[88:89], v[90:91]
	s_nop 0
	v_add_f32_e32 v80, v89, v92
	v_add_f32_e32 v84, v88, v80
	v_mov_b32_e32 v88, v67
	v_mov_b32_e32 v89, v69
	v_mov_b32_e32 v80, v85
	v_pk_mul_f32 v[80:81], v[88:89], v[80:81]
	v_mov_b32_e32 v85, v82
	v_add_f32_e32 v81, v81, v84
	v_add_f32_e32 v88, v80, v81
	v_mov_b32_e32 v80, v72
	v_mov_b32_e32 v81, v70
	v_mov_b32_e32 v84, v86
	v_pk_mul_f32 v[80:81], v[80:81], v[84:85]
	v_mov_b32_e32 v82, v87
	v_add_f32_e32 v81, v81, v88
	v_add_f32_e32 v84, v80, v81
	v_mov_b32_e32 v80, v73
	v_mov_b32_e32 v81, v71
	v_pk_mul_f32 v[80:81], v[80:81], v[82:83]
	s_nop 0
	v_add_f32_e32 v81, v81, v84
	v_add_f32_e32 v80, v80, v81
	ds_bpermute_b32 v81, v169, v80
	s_waitcnt lgkmcnt(0)
	v_add_f32_e32 v80, v80, v81
